# baseline (speedup 1.0000x reference)
; #define SBAR() __builtin_amdgcn_sched_barrier(0)
; #define SLOAD(i, t) do { const long rb_ = TROW(t); const char* vt_ = (const char*)Vh + rb_ * (LDK * 2); const char* kt_ = (const char*)Kh + rb_ * (LDK * 2); \
;     sr_[i].vs0 = *(const bf16x8*)(vt_ + lo0); sr_[i].vs1 = *(const bf16x8*)(vt_ + lo0 + 32 * LDK * 2); \
;     sr_[i].ks0 = *(const bf16x8*)(kt_ + lo0); sr_[i].ks1 = *(const bf16x8*)(kt_ + lo0 + 32 * LDK * 2); } while (0)
; __device__ __forceinline__ void finishSM(f32x16& p0, f32x16& p1, float alpha, float& l_reg, bf16x8& pa0, bf16x8& pa1, bf16x8& pa2, bf16x8& pa3) {
; #pragma unroll
;   for (int r = 0; r < 16; ++r) p1[r] = __builtin_amdgcn_exp2f(p1[r]);
;   float ps = 0;
; #pragma unroll
;   for (int r = 0; r < 16; ++r) ps += p0[r];
; #pragma unroll
;   for (int r = 0; r < 16; ++r) ps += p1[r];
;   { auto rr = __builtin_amdgcn_permlane32_swap(__float_as_uint(ps), __float_as_uint(ps), false, false);
;     ps = __uint_as_float(rr[0]) + __uint_as_float(rr[1]); }
;   l_reg = l_reg * alpha + ps;
;     ...
;   PK4(p0, 0, pa0); PK4(p0, 8, pa1); PK4(p1, 0, pa2); PK4(p1, 8, pa3);
;     ...
; }
; __device__ __forceinline__ void qkt(f32x16& p0, f32x16& p1, const bf16_t* Ks, const bf16x8* qr, int r32, int hi) {
;   p0 = f32x16{}; p1 = f32x16{};
; #pragma unroll
;   for (int d0 = 0; d0 < 8; ++d0) { int cb = (d0 * 16 + hi * 8) * 2;
;     bf16x8 b0 = *reinterpret_cast<const bf16x8*>((const char*)Ks + KSWZ(r32, cb));
;     bf16x8 b1 = *reinterpret_cast<const bf16x8*>((const char*)Ks + KSWZ(32 + r32, cb));
;     p0 = __builtin_amdgcn_mfma_f32_32x32x16_bf16(b0, qr[d0], p0, 0, 0, 0);
;     p1 = __builtin_amdgcn_mfma_f32_32x32x16_bf16(b1, qr[d0], p1, 0, 0, 0); }
; }
; template <bool META>
; __device__ __forceinline__ void attn_unit(const bf16_t* Q, bf16_t* Oo, const bf16_t* __restrict__ Kb, const bf16_t* __restrict__ Vb, int b, int kvh, int h, int qb, char* lds, const int tid, const float* qn, const float* RT) {
;     ...
;     SBAR(); qkt(pB0, pB1, (bf16_t*)((char*)K_lds + bc * SHM_K), qr, r32, hi);
;     finishSM(pA0, pA1, alA, l_reg, pa0, pa1, pa2, pa3); SBAR();
;     SLOAD(SO, j + 1);
;     SBAR();
;     pv_d0(o, vb0 + bp * (int)SHM_V, pa0, pa1, pa2, pa3); partialSM(pB0, pB1, m_reg, mnB, alB);
.LBB0_260:
	s_mov_b32 s6, s28
	v_sub_co_u32_e64 v66, s[0:1], s6, 1
	s_and_b64 s[0:1], s[0:1], exec
	v_readfirstlane_b32 s0, v66
	s_cselect_b32 s28, 2, s0
	s_lshl_b32 s9, s6, 14
	s_add_i32 s0, s9, 0
	v_add_u32_e32 v70, s0, v182
	ds_read_b128 v[66:69], v70 offset:49152
	ds_read_b128 v[70:73], v70 offset:57344
	v_add_u32_e32 v195, s0, v183
	ds_read_b128 v[210:213], v195 offset:49152
	ds_read_b128 v[214:217], v195 offset:57344
	v_add_u32_e32 v195, s0, v184
	ds_read_b128 v[218:221], v195 offset:49152
	ds_read_b128 v[222:225], v195 offset:57344
	v_add_u32_e32 v195, s0, v185
	ds_read_b128 v[226:229], v195 offset:49152
	ds_read_b128 v[198:201], v195 offset:57344
	v_add_u32_e32 v195, s0, v186
	s_waitcnt lgkmcnt(7)
	v_mfma_f32_32x32x16_bf16 v[82:97], v[66:69], v[98:101], 0
	v_exp_f32_e32 v144, v144
	v_exp_f32_e32 v145, v145
	v_exp_f32_e32 v142, v142
	v_exp_f32_e32 v143, v143
	v_exp_f32_e32 v140, v140
	v_exp_f32_e32 v141, v141
	v_exp_f32_e32 v138, v138
	s_waitcnt lgkmcnt(6)
	v_mfma_f32_32x32x16_bf16 v[66:81], v[70:73], v[98:101], 0
	v_exp_f32_e32 v139, v139
	v_exp_f32_e32 v136, v136
	v_exp_f32_e32 v137, v137
	v_exp_f32_e32 v134, v134
	v_exp_f32_e32 v135, v135
	v_exp_f32_e32 v132, v132
	v_exp_f32_e32 v133, v133
	s_waitcnt lgkmcnt(5)
	v_mfma_f32_32x32x16_bf16 v[82:97], v[210:213], v[102:105], v[82:97]
	v_exp_f32_e32 v130, v130
	v_exp_f32_e32 v131, v131
	s_waitcnt lgkmcnt(4)
	v_mfma_f32_32x32x16_bf16 v[66:81], v[214:217], v[102:105], v[66:81]
	ds_read_b128 v[210:213], v195 offset:49152
	ds_read_b128 v[214:217], v195 offset:57344
	v_add_u32_e32 v195, s0, v187
	s_waitcnt lgkmcnt(5)
	v_mfma_f32_32x32x16_bf16 v[82:97], v[218:221], v[106:109], v[82:97]
	s_waitcnt lgkmcnt(4)
	v_mfma_f32_32x32x16_bf16 v[66:81], v[222:225], v[106:109], v[66:81]
	ds_read_b128 v[218:221], v195 offset:49152
	ds_read_b128 v[222:225], v195 offset:57344
	v_add_u32_e32 v195, s0, v188
	s_waitcnt lgkmcnt(5)
	v_mfma_f32_32x32x16_bf16 v[82:97], v[226:229], v[110:113], v[82:97]
	s_waitcnt lgkmcnt(4)
	v_mfma_f32_32x32x16_bf16 v[66:81], v[198:201], v[110:113], v[66:81]
	ds_read_b128 v[226:229], v195 offset:49152
	ds_read_b128 v[198:201], v195 offset:57344
	v_add_u32_e32 v195, s0, v189
	s_waitcnt lgkmcnt(5)
	v_mfma_f32_32x32x16_bf16 v[82:97], v[210:213], v[114:117], v[82:97]
	s_waitcnt lgkmcnt(4)
	v_mfma_f32_32x32x16_bf16 v[66:81], v[214:217], v[114:117], v[66:81]
	ds_read_b128 v[210:213], v195 offset:49152
	ds_read_b128 v[214:217], v195 offset:57344
	v_add_f32_e32 v193, 0, v146
	v_add_f32_e32 v193, v147, v193
	v_add_f32_e32 v193, v148, v193
	v_add_f32_e32 v193, v159, v193
	v_add_f32_e32 v193, v160, v193
	s_waitcnt lgkmcnt(5)
	v_mfma_f32_32x32x16_bf16 v[82:97], v[218:221], v[118:121], v[82:97]
	v_add_f32_e32 v193, v209, v193
	v_add_f32_e32 v193, v149, v193
	v_add_f32_e32 v193, v161, v193
	v_add_f32_e32 v193, v151, v193
	v_add_f32_e32 v193, v153, v193
	s_waitcnt lgkmcnt(4)
	v_mfma_f32_32x32x16_bf16 v[66:81], v[222:225], v[118:121], v[66:81]
	v_add_f32_e32 v193, v154, v193
	v_add_f32_e32 v193, v157, v193
	v_add_f32_e32 v193, v152, v193
	v_add_f32_e32 v193, v155, v193
	v_add_f32_e32 v193, v156, v193
	s_waitcnt lgkmcnt(3)
	v_mfma_f32_32x32x16_bf16 v[82:97], v[226:229], v[122:125], v[82:97]
	v_add_f32_e32 v193, v158, v193
	v_add_f32_e32 v193, v144, v193
	v_add_f32_e32 v193, v145, v193
	v_add_f32_e32 v193, v142, v193
	v_add_f32_e32 v193, v143, v193
	s_waitcnt lgkmcnt(2)
	v_mfma_f32_32x32x16_bf16 v[66:81], v[198:201], v[122:125], v[66:81]
	v_add_f32_e32 v193, v140, v193
	v_add_f32_e32 v193, v141, v193
	v_add_f32_e32 v193, v138, v193
	v_add_f32_e32 v193, v139, v193
	v_add_f32_e32 v193, v136, v193
	v_add_f32_e32 v193, v137, v193
	s_waitcnt lgkmcnt(1)
	v_mfma_f32_32x32x16_bf16 v[82:97], v[210:213], v[126:129], v[82:97]
	v_add_f32_e32 v193, v134, v193
	v_add_f32_e32 v193, v135, v193
	v_add_f32_e32 v193, v132, v193
	v_add_f32_e32 v193, v133, v193
	v_add_f32_e32 v193, v130, v193
	v_add_f32_e32 v193, v131, v193
	v_mov_b32_e32 v195, v193
	s_waitcnt lgkmcnt(0)
	v_mfma_f32_32x32x16_bf16 v[66:81], v[214:217], v[126:129], v[66:81]
	v_cvt_pk_bf16_f32 v146, v146, v147
	v_cvt_pk_bf16_f32 v147, v148, v159
	v_cvt_pk_bf16_f32 v148, v160, v209
	v_permlane32_swap_b32_e32 v193, v195
	v_cvt_pk_bf16_f32 v149, v149, v161
	v_permlane32_swap_b32_e32 v146, v148
	v_cvt_pk_bf16_f32 v210, v151, v153
	v_cvt_pk_bf16_f32 v211, v154, v157
	v_cvt_pk_bf16_f32 v212, v152, v155
	v_cvt_pk_bf16_f32 v213, v156, v158
	v_cvt_pk_bf16_f32 v152, v144, v145
	v_cvt_pk_bf16_f32 v153, v142, v143
	v_cvt_pk_bf16_f32 v154, v140, v141
	v_cvt_pk_bf16_f32 v155, v138, v139
	v_cvt_pk_bf16_f32 v156, v136, v137
	v_cvt_pk_bf16_f32 v157, v134, v135
	v_cvt_pk_bf16_f32 v158, v132, v133
	v_cvt_pk_bf16_f32 v159, v130, v131
	v_permlane32_swap_b32_e32 v147, v149
	v_permlane32_swap_b32_e32 v210, v212
	v_permlane32_swap_b32_e32 v211, v213
	v_permlane32_swap_b32_e32 v152, v154
	v_permlane32_swap_b32_e32 v153, v155
	v_permlane32_swap_b32_e32 v156, v158
	v_permlane32_swap_b32_e32 v157, v159
	s_cmpk_lg_i32 s4, 0xfd
	s_cselect_b64 s[0:1], -1, 0
	s_cmpk_eq_i32 s4, 0xfd
	s_cselect_b64 s[40:41], -1, 0
	s_and_b64 s[10:11], s[40:41], exec
	s_cselect_b32 s11, s44, s91
	s_cselect_b32 s10, s31, s90
	s_lshl_b64 s[10:11], s[10:11], 9
	v_lshl_add_u64 v[130:131], v[168:169], 0, s[10:11]
	v_add_co_u32_e32 v134, vcc, s37, v130
	v_lshl_add_u64 v[138:139], v[170:171], 0, s[10:11]
	s_nop 0
	v_addc_co_u32_e32 v135, vcc, 0, v131, vcc
	v_add_co_u32_e32 v142, vcc, s37, v138
	global_load_dwordx4 v[130:133], v[130:131], off
	s_nop 0
	global_load_dwordx4 v[134:137], v[134:135], off
	v_addc_co_u32_e32 v143, vcc, 0, v139, vcc
	global_load_dwordx4 v[138:141], v[138:139], off
	s_nop 0
	global_load_dwordx4 v[142:145], v[142:143], off
	s_lshl_b32 s8, s28, 14
	v_add_u32_e32 v151, s8, v178
	ds_read_b64_tr_b16 v[214:215], v151 offset:0
	ds_read_b64_tr_b16 v[216:217], v151 offset:0x800
	ds_read_b64_tr_b16 v[218:219], v151 offset:0x1000
	ds_read_b64_tr_b16 v[220:221], v151 offset:0x1800
	ds_read_b64_tr_b16 v[222:223], v151 offset:0x2000
	ds_read_b64_tr_b16 v[224:225], v151 offset:0x2800
	ds_read_b64_tr_b16 v[226:227], v151 offset:0x3000
	ds_read_b64_tr_b16 v[228:229], v151 offset:0x3800
	s_waitcnt lgkmcnt(6)
; #define SBAR() __builtin_amdgcn_sched_barrier(0)
; __device__ __forceinline__ void partialSM(f32x16& p0, f32x16& p1, float& m_reg, float& mn, float& alpha) {
;   constexpr float C = ASCALE * 1.4426950408889634f;
;   float pmax = p0[0];
; #pragma unroll
;   for (int r = 1; r < 16; ++r) pmax = fmaxf(pmax, p0[r]);
; #pragma unroll
;   for (int r = 0; r < 16; ++r) pmax = fmaxf(pmax, p1[r]);
;   { auto rr = __builtin_amdgcn_permlane32_swap(__float_as_uint(pmax), __float_as_uint(pmax), false, false);
;     pmax = fmaxf(__uint_as_float(rr[0]), __uint_as_float(rr[1])); }
;   if (__builtin_expect(__all(pmax - m_reg <= ATHR / ASCALE), 1)) { mn = m_reg; alpha = 1.f; }
;   else { mn = fmaxf(m_reg, pmax); alpha = __builtin_amdgcn_exp2f((m_reg - mn) * C); m_reg = mn; }
; template <int D0> __device__ __forceinline__ void pv_one(f32x16& od, int vb, bf16x8 pa0, bf16x8 pa1, bf16x8 pa2, bf16x8 pa3) {
;   const s16x4 l0 = tr_read<v_rd_off(D0, 0, 0)>(vb), h0 = tr_read<v_rd_off(D0, 0, 1)>(vb), l1 = tr_read<v_rd_off(D0, 1, 0)>(vb), h1 = tr_read<v_rd_off(D0, 1, 1)>(vb);
;   const s16x4 l2 = tr_read<v_rd_off(D0, 2, 0)>(vb), h2 = tr_read<v_rd_off(D0, 2, 1)>(vb), l3 = tr_read<v_rd_off(D0, 3, 0)>(vb), h3 = tr_read<v_rd_off(D0, 3, 1)>(vb);
;   asm volatile("s_waitcnt lgkmcnt(0)" ::: "memory"); SBAR();
;     ...
;   od = __builtin_amdgcn_mfma_f32_32x32x16_bf16(pa0, PK(l0, h0), od, 0, 0, 0);
;   od = __builtin_amdgcn_mfma_f32_32x32x16_bf16(pa1, PK(l1, h1), od, 0, 0, 0);
;   od = __builtin_amdgcn_mfma_f32_32x32x16_bf16(pa2, PK(l2, h2), od, 0, 0, 0);
;   od = __builtin_amdgcn_mfma_f32_32x32x16_bf16(pa3, PK(l3, h3), od, 0, 0, 0);
;     ...
; }
; __device__ __forceinline__ void pv_d0(f32x16* o, int vb, bf16x8 pa0, bf16x8 pa1, bf16x8 pa2, bf16x8 pa3) {
;   pv_one<0>(o[0], vb, pa0, pa1, pa2, pa3); pv_one<1>(o[1], vb, pa0, pa1, pa2, pa3); pv_one<2>(o[2], vb, pa0, pa1, pa2, pa3); pv_one<3>(o[3], vb, pa0, pa1, pa2, pa3);
; }
	s_nop 0
	v_mfma_f32_32x32x16_bf16 v[2:17], v[146:149], v[214:217], v[2:17]
	ds_read_b64_tr_b16 v[214:215], v151 offset:0x200
	ds_read_b64_tr_b16 v[216:217], v151 offset:0xa00
	s_waitcnt lgkmcnt(6)
	v_mfma_f32_32x32x16_bf16 v[2:17], v[210:213], v[218:221], v[2:17]
	ds_read_b64_tr_b16 v[218:219], v151 offset:0x1200
	ds_read_b64_tr_b16 v[220:221], v151 offset:0x1a00
	s_waitcnt lgkmcnt(6)
	v_mfma_f32_32x32x16_bf16 v[2:17], v[152:155], v[222:225], v[2:17]
	ds_read_b64_tr_b16 v[222:223], v151 offset:0x2200
	ds_read_b64_tr_b16 v[224:225], v151 offset:0x2a00
	s_waitcnt lgkmcnt(6)
	v_mfma_f32_32x32x16_bf16 v[2:17], v[156:159], v[226:229], v[2:17]
	ds_read_b64_tr_b16 v[226:227], v151 offset:0x3200
	ds_read_b64_tr_b16 v[228:229], v151 offset:0x3a00
	s_waitcnt lgkmcnt(6)
	v_mfma_f32_32x32x16_bf16 v[50:65], v[146:149], v[214:217], v[50:65]
	ds_read_b64_tr_b16 v[214:215], v151 offset:0x400
	ds_read_b64_tr_b16 v[216:217], v151 offset:0xc00
	s_waitcnt lgkmcnt(6)
	v_mfma_f32_32x32x16_bf16 v[50:65], v[210:213], v[218:221], v[50:65]
	ds_read_b64_tr_b16 v[218:219], v151 offset:0x1400
	ds_read_b64_tr_b16 v[220:221], v151 offset:0x1c00
	s_waitcnt lgkmcnt(6)
	v_mfma_f32_32x32x16_bf16 v[50:65], v[152:155], v[222:225], v[50:65]
	ds_read_b64_tr_b16 v[222:223], v151 offset:0x2400
	ds_read_b64_tr_b16 v[224:225], v151 offset:0x2c00
	s_waitcnt lgkmcnt(6)
	v_mfma_f32_32x32x16_bf16 v[50:65], v[156:159], v[226:229], v[50:65]
	ds_read_b64_tr_b16 v[226:227], v151 offset:0x3400
	ds_read_b64_tr_b16 v[228:229], v151 offset:0x3c00
	s_waitcnt lgkmcnt(6)
	v_mfma_f32_32x32x16_bf16 v[34:49], v[146:149], v[214:217], v[34:49]
	ds_read_b64_tr_b16 v[214:215], v151 offset:0x600
	ds_read_b64_tr_b16 v[216:217], v151 offset:0xe00
	s_waitcnt lgkmcnt(6)
	v_mfma_f32_32x32x16_bf16 v[34:49], v[210:213], v[218:221], v[34:49]
	ds_read_b64_tr_b16 v[218:219], v151 offset:0x1600
	ds_read_b64_tr_b16 v[220:221], v151 offset:0x1e00
	s_waitcnt lgkmcnt(6)
	v_mfma_f32_32x32x16_bf16 v[34:49], v[152:155], v[222:225], v[34:49]
	ds_read_b64_tr_b16 v[222:223], v151 offset:0x2600
	ds_read_b64_tr_b16 v[224:225], v151 offset:0x2e00
	s_waitcnt lgkmcnt(6)
	v_mfma_f32_32x32x16_bf16 v[34:49], v[156:159], v[226:229], v[34:49]
	ds_read_b64_tr_b16 v[226:227], v151 offset:0x3600
	ds_read_b64_tr_b16 v[228:229], v151 offset:0x3e00
	s_waitcnt lgkmcnt(6)
	v_mfma_f32_32x32x16_bf16 v[18:33], v[146:149], v[214:217], v[18:33]
	v_max_f32_e32 v146, v83, v83
	v_max_f32_e32 v147, v82, v82
	v_max_f32_e32 v146, v147, v146
	v_max3_f32 v146, v146, v84, v85
	v_max3_f32 v146, v146, v86, v87
	v_max3_f32 v146, v146, v88, v89
	v_max3_f32 v146, v146, v90, v91
	v_max3_f32 v146, v146, v92, v93
	v_max3_f32 v146, v146, v94, v95
	v_max3_f32 v146, v146, v96, v97
	v_max3_f32 v146, v146, v66, v67
	s_waitcnt lgkmcnt(4)
	v_mfma_f32_32x32x16_bf16 v[18:33], v[210:213], v[218:221], v[18:33]
	v_max3_f32 v146, v146, v68, v69
	v_max3_f32 v146, v146, v70, v71
	v_max3_f32 v146, v146, v72, v73
	v_max3_f32 v146, v146, v74, v75
	v_max3_f32 v146, v146, v76, v77
	v_max3_f32 v146, v146, v78, v79
	v_max3_f32 v146, v146, v80, v81
	v_mov_b32_e32 v147, v146
	s_waitcnt lgkmcnt(2)
	v_mfma_f32_32x32x16_bf16 v[18:33], v[152:155], v[222:225], v[18:33]
	s_nop 0
	v_permlane32_swap_b32_e32 v146, v147
	v_max_f32_e32 v147, v147, v147
	v_max_f32_e32 v146, v146, v146
	v_max_f32_e32 v146, v146, v147
	v_sub_f32_e32 v147, v146, v150
	v_cmp_ge_f32_e32 vcc, s25, v147
	v_max_f32_e32 v147, v150, v150
	v_max_f32_e32 v146, v147, v146
	v_sub_f32_e32 v147, v150, v146
	s_cmp_eq_u64 vcc, exec
	v_mul_f32_e32 v147, 0x3e0293ee, v147
	s_waitcnt lgkmcnt(0)
	v_mfma_f32_32x32x16_bf16 v[18:33], v[156:159], v[226:229], v[18:33]
	s_cselect_b64 s[42:43], -1, 0
	v_exp_f32_e32 v147, v147
	s_add_i32 s7, s9, 0x4000
	s_cmp_lg_u32 s6, 2
	s_cselect_b32 s6, s7, 0
	s_add_i32 s10, s6, 0
	v_cndmask_b32_e64 v196, v147, 1.0, s[42:43]
	v_add_u32_e32 v147, s10, v176
	s_waitcnt vmcnt(0)
	s_waitcnt vmcnt(3)
	ds_write_b128 v147, v[130:133]
	v_add_u32_e32 v147, s10, v177
	s_waitcnt vmcnt(2)
	ds_write_b128 v147, v[134:137]
	v_add_u32_e32 v147, s10, v179
	s_waitcnt vmcnt(1)
	ds_write_b128 v147, v[138:141] offset:49152
	v_add_u32_e32 v147, s10, v180
	v_cmp_gt_f32_e32 vcc, 1.0, v196
	s_waitcnt vmcnt(0)
	ds_write_b128 v147, v[142:145] offset:49152
	s_cbranch_vccz .LBB0_264
	s_and_saveexec_b64 s[6:7], s[38:39]
	ds_write_b32 v190, v196 offset:128
	s_or_b64 exec, exec, s[6:7]
	s_waitcnt lgkmcnt(0)
	v_add_u32_e32 v147, v173, v181
	ds_read_b128 v[152:155], v147 offset:224
	ds_read_b128 v[156:159], v147 offset:192
	ds_read_b128 v[210:213], v147 offset:160
	ds_read_b128 v[214:217], v147 offset:128
	s_waitcnt lgkmcnt(3)
	v_pk_mul_f32 v[14:15], v[14:15], v[152:153]
	s_waitcnt lgkmcnt(2)
	v_pk_mul_f32 v[10:11], v[10:11], v[156:157]
	s_waitcnt lgkmcnt(1)
	v_pk_mul_f32 v[6:7], v[6:7], v[210:211]
	v_pk_mul_f32 v[16:17], v[16:17], v[154:155]
	v_pk_mul_f32 v[12:13], v[12:13], v[158:159]
	v_pk_mul_f32 v[8:9], v[8:9], v[212:213]
	s_waitcnt lgkmcnt(0)
	v_pk_mul_f32 v[4:5], v[4:5], v[216:217]
	v_pk_mul_f32 v[2:3], v[2:3], v[214:215]
	v_pk_mul_f32 v[62:63], v[62:63], v[152:153]
	v_pk_mul_f32 v[58:59], v[58:59], v[156:157]
	v_pk_mul_f32 v[54:55], v[54:55], v[210:211]
	v_pk_mul_f32 v[64:65], v[64:65], v[154:155]
	v_pk_mul_f32 v[60:61], v[60:61], v[158:159]
	v_pk_mul_f32 v[56:57], v[56:57], v[212:213]
	v_pk_mul_f32 v[52:53], v[52:53], v[216:217]
	v_pk_mul_f32 v[50:51], v[50:51], v[214:215]
	v_pk_mul_f32 v[46:47], v[46:47], v[152:153]
	v_pk_mul_f32 v[42:43], v[42:43], v[156:157]
	v_pk_mul_f32 v[38:39], v[38:39], v[210:211]
	v_pk_mul_f32 v[48:49], v[48:49], v[154:155]
	v_pk_mul_f32 v[44:45], v[44:45], v[158:159]
	v_pk_mul_f32 v[40:41], v[40:41], v[212:213]
	v_pk_mul_f32 v[36:37], v[36:37], v[216:217]
	v_pk_mul_f32 v[34:35], v[34:35], v[214:215]
	v_pk_mul_f32 v[30:31], v[30:31], v[152:153]
	v_pk_mul_f32 v[26:27], v[26:27], v[156:157]
	v_pk_mul_f32 v[22:23], v[22:23], v[210:211]
	v_pk_mul_f32 v[32:33], v[32:33], v[154:155]
	v_pk_mul_f32 v[28:29], v[28:29], v[158:159]
	v_pk_mul_f32 v[24:25], v[24:25], v[212:213]
	v_pk_mul_f32 v[20:21], v[20:21], v[216:217]
	v_pk_mul_f32 v[18:19], v[18:19], v[214:215]
; __device__ __forceinline__ void partialSM(f32x16& p0, f32x16& p1, float& m_reg, float& mn, float& alpha) {
;     ...
;   float mnC = -mn * C;
; #pragma unroll
;   for (int r = 0; r < 16; ++r) p0[r] = fmaf(p0[r], C, mnC);
; #pragma unroll
;   for (int r = 0; r < 16; ++r) p1[r] = fmaf(p1[r], C, mnC);
; #pragma unroll
;   for (int r = 0; r < 16; ++r) p0[r] = __builtin_amdgcn_exp2f(p0[r]);
.LBB0_264:
	v_cndmask_b32_e64 v209, v146, v150, s[42:43]
	v_mul_f32_e32 v154, 0xbe0293ee, v209
	s_add_i32 s4, s4, 2
	v_fmamk_f32 v82, v82, 0x3e0293ee, v154
	v_fmamk_f32 v83, v83, 0x3e0293ee, v154
	v_fmamk_f32 v84, v84, 0x3e0293ee, v154
	v_fmamk_f32 v85, v85, 0x3e0293ee, v154
	v_fmamk_f32 v86, v86, 0x3e0293ee, v154
	v_fmamk_f32 v87, v87, 0x3e0293ee, v154
	v_fmamk_f32 v88, v88, 0x3e0293ee, v154
	v_fmamk_f32 v89, v89, 0x3e0293ee, v154
	v_fmamk_f32 v90, v90, 0x3e0293ee, v154
	v_fmamk_f32 v91, v91, 0x3e0293ee, v154
	v_fmamk_f32 v92, v92, 0x3e0293ee, v154
	v_fmamk_f32 v93, v93, 0x3e0293ee, v154
	v_fmamk_f32 v94, v94, 0x3e0293ee, v154
	v_fmamk_f32 v95, v95, 0x3e0293ee, v154
	v_fmamk_f32 v96, v96, 0x3e0293ee, v154
	v_fmamk_f32 v97, v97, 0x3e0293ee, v154
	v_fmamk_f32 v155, v66, 0x3e0293ee, v154
	v_fmamk_f32 v156, v67, 0x3e0293ee, v154
	v_fmamk_f32 v157, v68, 0x3e0293ee, v154
	v_fmamk_f32 v158, v69, 0x3e0293ee, v154
	v_fmamk_f32 v159, v70, 0x3e0293ee, v154
	v_fmamk_f32 v160, v71, 0x3e0293ee, v154
	v_fmamk_f32 v161, v72, 0x3e0293ee, v154
	v_fmamk_f32 v198, v73, 0x3e0293ee, v154
	v_fmamk_f32 v199, v74, 0x3e0293ee, v154
	v_fmamk_f32 v200, v75, 0x3e0293ee, v154
	v_fmamk_f32 v201, v76, 0x3e0293ee, v154
	v_fmamk_f32 v202, v77, 0x3e0293ee, v154
	v_fmamk_f32 v203, v78, 0x3e0293ee, v154
	v_fmamk_f32 v204, v79, 0x3e0293ee, v154
	v_fmamk_f32 v205, v80, 0x3e0293ee, v154
	v_fmac_f32_e32 v154, 0x3e0293ee, v81
	v_exp_f32_e32 v206, v82
	v_exp_f32_e32 v207, v83
	v_exp_f32_e32 v212, v84
	v_exp_f32_e32 v213, v85
	v_exp_f32_e32 v214, v86
	v_exp_f32_e32 v215, v87
	v_exp_f32_e32 v216, v88
	v_exp_f32_e32 v217, v89
	v_exp_f32_e32 v218, v90
	v_exp_f32_e32 v219, v91
	v_exp_f32_e32 v220, v92
	v_exp_f32_e32 v221, v93
	v_exp_f32_e32 v222, v94
	v_exp_f32_e32 v223, v95
	v_exp_f32_e32 v224, v96
	v_exp_f32_e32 v225, v97
	s_waitcnt lgkmcnt(0)
	s_barrier
; #define SBAR() __builtin_amdgcn_sched_barrier(0)
; #define SLOAD(i, t) do { const long rb_ = TROW(t); const char* vt_ = (const char*)Vh + rb_ * (LDK * 2); const char* kt_ = (const char*)Kh + rb_ * (LDK * 2); \
;     sr_[i].vs0 = *(const bf16x8*)(vt_ + lo0); sr_[i].vs1 = *(const bf16x8*)(vt_ + lo0 + 32 * LDK * 2); \
;     sr_[i].ks0 = *(const bf16x8*)(kt_ + lo0); sr_[i].ks1 = *(const bf16x8*)(kt_ + lo0 + 32 * LDK * 2); } while (0)
; __device__ __forceinline__ void finishSM(f32x16& p0, f32x16& p1, float alpha, float& l_reg, bf16x8& pa0, bf16x8& pa1, bf16x8& pa2, bf16x8& pa3) {
; #pragma unroll
;   for (int r = 0; r < 16; ++r) p1[r] = __builtin_amdgcn_exp2f(p1[r]);
;   float ps = 0;
; #pragma unroll
;   for (int r = 0; r < 16; ++r) ps += p0[r];
; #pragma unroll
;   for (int r = 0; r < 16; ++r) ps += p1[r];
;   { auto rr = __builtin_amdgcn_permlane32_swap(__float_as_uint(ps), __float_as_uint(ps), false, false);
;     ps = __uint_as_float(rr[0]) + __uint_as_float(rr[1]); }
;   l_reg = l_reg * alpha + ps;
;     ...
;   PK4(p0, 0, pa0); PK4(p0, 8, pa1); PK4(p1, 0, pa2); PK4(p1, 8, pa3);
;     ...
; }
; __device__ __forceinline__ void qkt(f32x16& p0, f32x16& p1, const bf16_t* Ks, const bf16x8* qr, int r32, int hi) {
;   p0 = f32x16{}; p1 = f32x16{};
; #pragma unroll
;   for (int d0 = 0; d0 < 8; ++d0) { int cb = (d0 * 16 + hi * 8) * 2;
;     bf16x8 b0 = *reinterpret_cast<const bf16x8*>((const char*)Ks + KSWZ(r32, cb));
;     bf16x8 b1 = *reinterpret_cast<const bf16x8*>((const char*)Ks + KSWZ(32 + r32, cb));
;     p0 = __builtin_amdgcn_mfma_f32_32x32x16_bf16(b0, qr[d0], p0, 0, 0, 0);
;     p1 = __builtin_amdgcn_mfma_f32_32x32x16_bf16(b1, qr[d0], p1, 0, 0, 0); }
; }
; template <bool META>
; __device__ __forceinline__ void attn_unit(const bf16_t* Q, bf16_t* Oo, const bf16_t* __restrict__ Kb, const bf16_t* __restrict__ Vb, int b, int kvh, int h, int qb, char* lds, const int tid, const float* qn, const float* RT) {
;     ...
;     SBAR(); qkt(pA0, pA1, (bf16_t*)((char*)K_lds + bn * SHM_K), qr, r32, hi);
;     if (j + 1 == NT - 1) mask_last(pA0, pA1);
;     finishSM(pB0, pB1, alB, l_reg, pa0, pa1, pa2, pa3); SBAR();
;     if (j + 2 < NT) SLOAD(SE, j + 2);
	v_add_u32_e32 v70, s10, v182
	ds_read_b128 v[66:69], v70 offset:49152
	ds_read_b128 v[82:85], v70 offset:57344
	v_add_u32_e32 v211, s10, v183
	ds_read_b128 v[146:149], v211 offset:49152
	ds_read_b128 v[150:153], v211 offset:57344
	v_add_u32_e32 v211, s10, v184
	ds_read_b128 v[130:133], v211 offset:49152
	ds_read_b128 v[134:137], v211 offset:57344
	v_add_u32_e32 v211, s10, v185
	ds_read_b128 v[138:141], v211 offset:49152
	ds_read_b128 v[142:145], v211 offset:57344
	v_add_u32_e32 v211, s10, v186
	v_exp_f32_e32 v155, v155
	s_waitcnt lgkmcnt(7)
	v_mfma_f32_32x32x16_bf16 v[66:81], v[66:69], v[98:101], 0
	v_exp_f32_e32 v156, v156
	v_exp_f32_e32 v157, v157
	v_exp_f32_e32 v158, v158
	v_exp_f32_e32 v159, v159
	v_exp_f32_e32 v160, v160
	v_exp_f32_e32 v161, v161
	v_exp_f32_e32 v198, v198
	s_waitcnt lgkmcnt(6)
	v_mfma_f32_32x32x16_bf16 v[82:97], v[82:85], v[98:101], 0
	v_exp_f32_e32 v199, v199
	v_exp_f32_e32 v200, v200
	v_exp_f32_e32 v201, v201
	v_exp_f32_e32 v202, v202
	v_exp_f32_e32 v203, v203
	v_exp_f32_e32 v204, v204
	v_exp_f32_e32 v205, v205
	s_waitcnt lgkmcnt(5)
	v_mfma_f32_32x32x16_bf16 v[66:81], v[146:149], v[102:105], v[66:81]
	v_exp_f32_e32 v226, v154
	v_cvt_pk_bf16_f32 v154, v155, v156
	s_waitcnt lgkmcnt(4)
	v_mfma_f32_32x32x16_bf16 v[82:97], v[150:153], v[102:105], v[82:97]
	ds_read_b128 v[146:149], v211 offset:49152
	ds_read_b128 v[150:153], v211 offset:57344
	v_add_u32_e32 v211, s10, v187
	s_waitcnt lgkmcnt(5)
	v_mfma_f32_32x32x16_bf16 v[66:81], v[130:133], v[106:109], v[66:81]
	s_waitcnt lgkmcnt(4)
	v_mfma_f32_32x32x16_bf16 v[82:97], v[134:137], v[106:109], v[82:97]
	ds_read_b128 v[130:133], v211 offset:49152
	ds_read_b128 v[134:137], v211 offset:57344
	v_add_u32_e32 v211, s10, v188
	s_waitcnt lgkmcnt(5)
	v_mfma_f32_32x32x16_bf16 v[66:81], v[138:141], v[110:113], v[66:81]
	s_waitcnt lgkmcnt(4)
	v_mfma_f32_32x32x16_bf16 v[82:97], v[142:145], v[110:113], v[82:97]
	ds_read_b128 v[138:141], v211 offset:49152
	ds_read_b128 v[142:145], v211 offset:57344
	v_add_u32_e32 v211, s10, v189
	s_waitcnt lgkmcnt(5)
	v_mfma_f32_32x32x16_bf16 v[66:81], v[146:149], v[114:117], v[66:81]
	s_waitcnt lgkmcnt(4)
	v_mfma_f32_32x32x16_bf16 v[82:97], v[150:153], v[114:117], v[82:97]
	ds_read_b128 v[146:149], v211 offset:49152
	ds_read_b128 v[150:153], v211 offset:57344
	v_add_f32_e32 v210, 0, v206
	v_add_f32_e32 v210, v207, v210
	v_add_f32_e32 v210, v212, v210
	v_add_f32_e32 v210, v213, v210
	v_add_f32_e32 v210, v214, v210
	s_waitcnt lgkmcnt(5)
	v_mfma_f32_32x32x16_bf16 v[66:81], v[130:133], v[118:121], v[66:81]
	v_add_f32_e32 v210, v215, v210
	v_add_f32_e32 v210, v216, v210
	v_add_f32_e32 v210, v217, v210
	v_add_f32_e32 v210, v218, v210
	v_add_f32_e32 v210, v219, v210
	s_waitcnt lgkmcnt(4)
	v_mfma_f32_32x32x16_bf16 v[82:97], v[134:137], v[118:121], v[82:97]
	v_add_f32_e32 v210, v220, v210
	v_add_f32_e32 v210, v221, v210
	v_add_f32_e32 v210, v222, v210
	v_add_f32_e32 v210, v223, v210
	v_add_f32_e32 v210, v224, v210
	s_waitcnt lgkmcnt(3)
	v_mfma_f32_32x32x16_bf16 v[66:81], v[138:141], v[122:125], v[66:81]
	v_add_f32_e32 v210, v225, v210
	v_add_f32_e32 v210, v155, v210
	v_add_f32_e32 v210, v156, v210
	v_add_f32_e32 v210, v157, v210
	v_add_f32_e32 v210, v158, v210
	s_waitcnt lgkmcnt(2)
	v_mfma_f32_32x32x16_bf16 v[82:97], v[142:145], v[122:125], v[82:97]
	v_add_f32_e32 v210, v159, v210
	v_add_f32_e32 v210, v160, v210
	v_add_f32_e32 v210, v161, v210
	v_add_f32_e32 v210, v198, v210
	v_add_f32_e32 v210, v199, v210
	s_waitcnt lgkmcnt(1)
	v_mfma_f32_32x32x16_bf16 v[66:81], v[146:149], v[126:129], v[66:81]
	v_add_f32_e32 v210, v200, v210
	v_add_f32_e32 v210, v201, v210
	v_add_f32_e32 v210, v202, v210
	v_add_f32_e32 v210, v203, v210
	v_add_f32_e32 v210, v204, v210
	v_add_f32_e32 v210, v205, v210
	s_waitcnt lgkmcnt(0)
	v_mfma_f32_32x32x16_bf16 v[82:97], v[150:153], v[126:129], v[82:97]
	v_add_f32_e32 v210, v226, v210
	v_mov_b32_e32 v211, v210
	v_cvt_pk_bf16_f32 v146, v206, v207
	v_cvt_pk_bf16_f32 v147, v212, v213
	v_cvt_pk_bf16_f32 v148, v214, v215
	v_cvt_pk_bf16_f32 v149, v216, v217
	v_cvt_pk_bf16_f32 v150, v218, v219
	v_cvt_pk_bf16_f32 v151, v220, v221
	v_cvt_pk_bf16_f32 v152, v222, v223
	v_cvt_pk_bf16_f32 v153, v224, v225
	v_cvt_pk_bf16_f32 v155, v157, v158
	v_cvt_pk_bf16_f32 v156, v159, v160
	v_cvt_pk_bf16_f32 v157, v161, v198
	v_cvt_pk_bf16_f32 v158, v199, v200
	v_cvt_pk_bf16_f32 v159, v201, v202
	v_cvt_pk_bf16_f32 v160, v203, v204
	v_cvt_pk_bf16_f32 v161, v205, v226
	v_permlane32_swap_b32_e32 v210, v211
	v_permlane32_swap_b32_e32 v146, v148
	v_permlane32_swap_b32_e32 v147, v149
	v_permlane32_swap_b32_e32 v150, v152
	v_permlane32_swap_b32_e32 v151, v153
	v_permlane32_swap_b32_e32 v154, v156
	v_permlane32_swap_b32_e32 v155, v157
	v_permlane32_swap_b32_e32 v158, v160
	v_permlane32_swap_b32_e32 v159, v161
	s_andn2_b64 vcc, exec, s[0:1]
	s_cbranch_vccnz .LBB0_266
	s_add_u32 s0, s90, 64
	s_addc_u32 s1, s91, 0
	s_cmpk_lt_u32 s4, 0xfe
	s_cselect_b32 s1, s1, s44
	s_cselect_b32 s0, s0, s31
	s_lshl_b64 s[0:1], s[0:1], 9
	v_lshl_add_u64 v[130:131], v[168:169], 0, s[0:1]
	v_add_co_u32_e32 v134, vcc, 0x4000, v130
	v_lshl_add_u64 v[138:139], v[170:171], 0, s[0:1]
	s_nop 0
	v_addc_co_u32_e32 v135, vcc, 0, v131, vcc
	v_add_co_u32_e32 v142, vcc, 0x4000, v138
	global_load_dwordx4 v[130:133], v[130:131], off
	s_nop 0
	global_load_dwordx4 v[134:137], v[134:135], off
	v_addc_co_u32_e32 v143, vcc, 0, v139, vcc
	global_load_dwordx4 v[138:141], v[138:139], off
	s_nop 0
	global_load_dwordx4 v[142:145], v[142:143], off
